# hand-written gate/up epilogue (packed f32 silu*up, v_permlane32_swap exchange) for all but a block's last job
# speedup vs baseline: 1.0127x; 1.0056x over previous
.LBB0_160:
	v_readlane_b32 s98, v255, 6
	v_readlane_b32 s99, v254, 40
	s_add_i32 s98, s0, s98
	s_cmp_ge_i32 s98, s99
	s_cbranch_scc1 .Lgu_slow
	v_mfma_f32_32x32x16_bf16 a[16:31], v[132:135], v[112:115], a[16:31]
	v_mfma_f32_32x32x16_bf16 a[32:47], v[132:135], v[80:83], a[32:47]
	v_mfma_f32_32x32x16_bf16 a[0:15], v[132:135], v[128:131], a[0:15]
	v_or_b32_e32 v129, s2, v161
	v_or_b32_e32 v128, s1, v162
	v_add_u32_e32 v133, v163, v129
	v_readlane_b32 s2, v253, 61
	v_readlane_b32 s3, v253, 62
	v_ashrrev_i32_e32 v130, 1, v128
	s_nop 0
	v_mov_b64_e32 v[128:129], s[2:3]
	s_movk_i32 s1, 0x1600
	v_mad_i64_i32 v[134:135], s[2:3], v133, s1, v[128:129]
	v_ashrrev_i32_e32 v131, 31, v130
	v_lshlrev_b64 v[130:131], 1, v[130:131]
	v_lshl_add_u64 v[96:97], v[134:135], 0, v[130:131]
	v_and_b32_e32 v192, 32, v160
	v_lshl_add_u64 v[96:97], v[96:97], 0, v[192:193]
	v_add_u32_e32 v136, 32, v133
	v_mad_i64_i32 v[136:137], s[4:5], v136, s1, v[128:129]
	v_lshl_add_u64 v[136:137], v[136:137], 0, v[130:131]
	v_lshl_add_u64 v[66:67], v[136:137], 0, v[192:193]
	v_add_u32_e32 v100, 64, v133
	v_mad_i64_i32 v[100:101], s[4:5], v100, s1, v[128:129]
	v_lshl_add_u64 v[100:101], v[100:101], 0, v[130:131]
	v_lshl_add_u64 v[64:65], v[100:101], 0, v[192:193]
	v_mov_b32_e32 v154, 0xbfb8aa3b
	v_mov_b32_e32 v155, 0xbfb8aa3b
	v_accvgpr_read_b32 v0, a80
	v_accvgpr_read_b32 v1, a81
	v_accvgpr_read_b32 v2, a82
	v_accvgpr_read_b32 v3, a83
	v_accvgpr_read_b32 v4, a84
	v_accvgpr_read_b32 v5, a85
	v_accvgpr_read_b32 v6, a86
	v_accvgpr_read_b32 v7, a87
	v_accvgpr_read_b32 v8, a88
	v_accvgpr_read_b32 v9, a89
	v_accvgpr_read_b32 v10, a90
	v_accvgpr_read_b32 v11, a91
	v_accvgpr_read_b32 v12, a92
	v_accvgpr_read_b32 v13, a93
	v_accvgpr_read_b32 v14, a94
	v_accvgpr_read_b32 v15, a95
	v_pk_mul_f32 v[32:33], v[0:1], v[154:155]
	v_pk_mul_f32 v[34:35], v[2:3], v[154:155]
	v_pk_mul_f32 v[36:37], v[4:5], v[154:155]
	v_pk_mul_f32 v[38:39], v[6:7], v[154:155]
	v_pk_mul_f32 v[40:41], v[8:9], v[154:155]
	v_pk_mul_f32 v[42:43], v[10:11], v[154:155]
	v_pk_mul_f32 v[44:45], v[12:13], v[154:155]
	v_pk_mul_f32 v[46:47], v[14:15], v[154:155]
	v_accvgpr_read_b32 v16, a96
	v_accvgpr_read_b32 v17, a97
	v_accvgpr_read_b32 v18, a98
	v_accvgpr_read_b32 v19, a99
	v_accvgpr_read_b32 v20, a100
	v_accvgpr_read_b32 v21, a101
	v_accvgpr_read_b32 v22, a102
	v_accvgpr_read_b32 v23, a103
	v_accvgpr_read_b32 v24, a104
	v_accvgpr_read_b32 v25, a105
	v_accvgpr_read_b32 v26, a106
	v_accvgpr_read_b32 v27, a107
	v_accvgpr_read_b32 v28, a108
	v_accvgpr_read_b32 v29, a109
	v_accvgpr_read_b32 v30, a110
	v_accvgpr_read_b32 v31, a111
	v_exp_f32_e32 v32, v32
	v_exp_f32_e32 v33, v33
	v_exp_f32_e32 v34, v34
	v_exp_f32_e32 v35, v35
	v_exp_f32_e32 v36, v36
	v_exp_f32_e32 v37, v37
	v_exp_f32_e32 v38, v38
	v_exp_f32_e32 v39, v39
	v_exp_f32_e32 v40, v40
	v_exp_f32_e32 v41, v41
	v_exp_f32_e32 v42, v42
	v_exp_f32_e32 v43, v43
	v_exp_f32_e32 v44, v44
	v_exp_f32_e32 v45, v45
	v_exp_f32_e32 v46, v46
	v_exp_f32_e32 v47, v47
	s_nop 0
	v_pk_add_f32 v[32:33], v[32:33], 1.0 op_sel_hi:[1,0]
	v_pk_add_f32 v[34:35], v[34:35], 1.0 op_sel_hi:[1,0]
	v_pk_add_f32 v[36:37], v[36:37], 1.0 op_sel_hi:[1,0]
	v_pk_add_f32 v[38:39], v[38:39], 1.0 op_sel_hi:[1,0]
	v_pk_add_f32 v[40:41], v[40:41], 1.0 op_sel_hi:[1,0]
	v_pk_add_f32 v[42:43], v[42:43], 1.0 op_sel_hi:[1,0]
	v_pk_add_f32 v[44:45], v[44:45], 1.0 op_sel_hi:[1,0]
	v_pk_add_f32 v[46:47], v[46:47], 1.0 op_sel_hi:[1,0]
	v_rcp_f32_e32 v32, v32
	v_rcp_f32_e32 v33, v33
	v_rcp_f32_e32 v34, v34
	v_rcp_f32_e32 v35, v35
	v_rcp_f32_e32 v36, v36
	v_rcp_f32_e32 v37, v37
	v_rcp_f32_e32 v38, v38
	v_rcp_f32_e32 v39, v39
	v_rcp_f32_e32 v40, v40
	v_rcp_f32_e32 v41, v41
	v_rcp_f32_e32 v42, v42
	v_rcp_f32_e32 v43, v43
	v_rcp_f32_e32 v44, v44
	v_rcp_f32_e32 v45, v45
	v_rcp_f32_e32 v46, v46
	v_rcp_f32_e32 v47, v47
	s_nop 0
	v_pk_mul_f32 v[32:33], v[0:1], v[32:33]
	v_pk_mul_f32 v[34:35], v[2:3], v[34:35]
	v_pk_mul_f32 v[36:37], v[4:5], v[36:37]
	v_pk_mul_f32 v[38:39], v[6:7], v[38:39]
	v_pk_mul_f32 v[40:41], v[8:9], v[40:41]
	v_pk_mul_f32 v[42:43], v[10:11], v[42:43]
	v_pk_mul_f32 v[44:45], v[12:13], v[44:45]
	v_pk_mul_f32 v[46:47], v[14:15], v[46:47]
	v_pk_mul_f32 v[32:33], v[32:33], v[16:17]
	v_pk_mul_f32 v[34:35], v[34:35], v[18:19]
	v_pk_mul_f32 v[36:37], v[36:37], v[20:21]
	v_pk_mul_f32 v[38:39], v[38:39], v[22:23]
	v_pk_mul_f32 v[40:41], v[40:41], v[24:25]
	v_pk_mul_f32 v[42:43], v[42:43], v[26:27]
	v_pk_mul_f32 v[44:45], v[44:45], v[28:29]
	v_pk_mul_f32 v[46:47], v[46:47], v[30:31]
	v_cvt_pk_bf16_f32 v48, v32, v33
	v_cvt_pk_bf16_f32 v49, v34, v35
	v_cvt_pk_bf16_f32 v52, v36, v37
	v_cvt_pk_bf16_f32 v53, v38, v39
	v_cvt_pk_bf16_f32 v50, v40, v41
	v_cvt_pk_bf16_f32 v51, v42, v43
	v_cvt_pk_bf16_f32 v54, v44, v45
	v_cvt_pk_bf16_f32 v55, v46, v47
	s_nop 1
	v_permlane32_swap_b32_e32 v48, v50
	v_permlane32_swap_b32_e32 v49, v51
	v_permlane32_swap_b32_e32 v52, v54
	v_permlane32_swap_b32_e32 v53, v55
	s_nop 1
	global_store_dwordx4 v[96:97], v[48:51], off
	global_store_dwordx4 v[96:97], v[52:55], off offset:16
	v_accvgpr_read_b32 v68, a48
	v_accvgpr_read_b32 v69, a49
	v_accvgpr_read_b32 v70, a50
	v_accvgpr_read_b32 v71, a51
	v_accvgpr_read_b32 v72, a52
	v_accvgpr_read_b32 v73, a53
	v_accvgpr_read_b32 v74, a54
	v_accvgpr_read_b32 v75, a55
	v_accvgpr_read_b32 v76, a56
	v_accvgpr_read_b32 v77, a57
	v_accvgpr_read_b32 v78, a58
	v_accvgpr_read_b32 v79, a59
	v_accvgpr_read_b32 v80, a60
	v_accvgpr_read_b32 v81, a61
	v_accvgpr_read_b32 v82, a62
	v_accvgpr_read_b32 v83, a63
	v_pk_mul_f32 v[138:139], v[68:69], v[154:155]
	v_pk_mul_f32 v[140:141], v[70:71], v[154:155]
	v_pk_mul_f32 v[142:143], v[72:73], v[154:155]
	v_pk_mul_f32 v[144:145], v[74:75], v[154:155]
	v_pk_mul_f32 v[146:147], v[76:77], v[154:155]
	v_pk_mul_f32 v[148:149], v[78:79], v[154:155]
	v_pk_mul_f32 v[150:151], v[80:81], v[154:155]
	v_pk_mul_f32 v[152:153], v[82:83], v[154:155]
	v_accvgpr_read_b32 v104, a112
	v_accvgpr_read_b32 v105, a113
	v_accvgpr_read_b32 v106, a114
	v_accvgpr_read_b32 v107, a115
	v_accvgpr_read_b32 v108, a116
	v_accvgpr_read_b32 v109, a117
	v_accvgpr_read_b32 v110, a118
	v_accvgpr_read_b32 v111, a119
	v_accvgpr_read_b32 v112, a120
	v_accvgpr_read_b32 v113, a121
	v_accvgpr_read_b32 v114, a122
	v_accvgpr_read_b32 v115, a123
	v_accvgpr_read_b32 v116, a124
	v_accvgpr_read_b32 v117, a125
	v_accvgpr_read_b32 v118, a126
	v_accvgpr_read_b32 v119, a127
	v_exp_f32_e32 v138, v138
	v_exp_f32_e32 v139, v139
	v_exp_f32_e32 v140, v140
	v_exp_f32_e32 v141, v141
	v_exp_f32_e32 v142, v142
	v_exp_f32_e32 v143, v143
	v_exp_f32_e32 v144, v144
	v_exp_f32_e32 v145, v145
	v_exp_f32_e32 v146, v146
	v_exp_f32_e32 v147, v147
	v_exp_f32_e32 v148, v148
	v_exp_f32_e32 v149, v149
	v_exp_f32_e32 v150, v150
	v_exp_f32_e32 v151, v151
	v_exp_f32_e32 v152, v152
	v_exp_f32_e32 v153, v153
	s_nop 0
	v_pk_add_f32 v[138:139], v[138:139], 1.0 op_sel_hi:[1,0]
	v_pk_add_f32 v[140:141], v[140:141], 1.0 op_sel_hi:[1,0]
	v_pk_add_f32 v[142:143], v[142:143], 1.0 op_sel_hi:[1,0]
	v_pk_add_f32 v[144:145], v[144:145], 1.0 op_sel_hi:[1,0]
	v_pk_add_f32 v[146:147], v[146:147], 1.0 op_sel_hi:[1,0]
	v_pk_add_f32 v[148:149], v[148:149], 1.0 op_sel_hi:[1,0]
	v_pk_add_f32 v[150:151], v[150:151], 1.0 op_sel_hi:[1,0]
	v_pk_add_f32 v[152:153], v[152:153], 1.0 op_sel_hi:[1,0]
	v_rcp_f32_e32 v138, v138
	v_rcp_f32_e32 v139, v139
	v_rcp_f32_e32 v140, v140
	v_rcp_f32_e32 v141, v141
	v_rcp_f32_e32 v142, v142
	v_rcp_f32_e32 v143, v143
	v_rcp_f32_e32 v144, v144
	v_rcp_f32_e32 v145, v145
	v_rcp_f32_e32 v146, v146
	v_rcp_f32_e32 v147, v147
	v_rcp_f32_e32 v148, v148
	v_rcp_f32_e32 v149, v149
	v_rcp_f32_e32 v150, v150
	v_rcp_f32_e32 v151, v151
	v_rcp_f32_e32 v152, v152
	v_rcp_f32_e32 v153, v153
	s_nop 0
	v_pk_mul_f32 v[138:139], v[68:69], v[138:139]
	v_pk_mul_f32 v[140:141], v[70:71], v[140:141]
	v_pk_mul_f32 v[142:143], v[72:73], v[142:143]
	v_pk_mul_f32 v[144:145], v[74:75], v[144:145]
	v_pk_mul_f32 v[146:147], v[76:77], v[146:147]
	v_pk_mul_f32 v[148:149], v[78:79], v[148:149]
	v_pk_mul_f32 v[150:151], v[80:81], v[150:151]
	v_pk_mul_f32 v[152:153], v[82:83], v[152:153]
	v_pk_mul_f32 v[138:139], v[138:139], v[104:105]
	v_pk_mul_f32 v[140:141], v[140:141], v[106:107]
	v_pk_mul_f32 v[142:143], v[142:143], v[108:109]
	v_pk_mul_f32 v[144:145], v[144:145], v[110:111]
	v_pk_mul_f32 v[146:147], v[146:147], v[112:113]
	v_pk_mul_f32 v[148:149], v[148:149], v[114:115]
	v_pk_mul_f32 v[150:151], v[150:151], v[116:117]
	v_pk_mul_f32 v[152:153], v[152:153], v[118:119]
	v_cvt_pk_bf16_f32 v56, v138, v139
	v_cvt_pk_bf16_f32 v57, v140, v141
	v_cvt_pk_bf16_f32 v60, v142, v143
	v_cvt_pk_bf16_f32 v61, v144, v145
	v_cvt_pk_bf16_f32 v58, v146, v147
	v_cvt_pk_bf16_f32 v59, v148, v149
	v_cvt_pk_bf16_f32 v62, v150, v151
	v_cvt_pk_bf16_f32 v63, v152, v153
	s_nop 1
	v_permlane32_swap_b32_e32 v56, v58
	v_permlane32_swap_b32_e32 v57, v59
	v_permlane32_swap_b32_e32 v60, v62
	v_permlane32_swap_b32_e32 v61, v63
	s_nop 1
	global_store_dwordx4 v[66:67], v[56:59], off
	global_store_dwordx4 v[66:67], v[60:63], off offset:16
	v_accvgpr_read_b32 v0, a64
	v_accvgpr_read_b32 v1, a65
	v_accvgpr_read_b32 v2, a66
	v_accvgpr_read_b32 v3, a67
	v_accvgpr_read_b32 v4, a68
	v_accvgpr_read_b32 v5, a69
	v_accvgpr_read_b32 v6, a70
	v_accvgpr_read_b32 v7, a71
	v_accvgpr_read_b32 v8, a72
	v_accvgpr_read_b32 v9, a73
	v_accvgpr_read_b32 v10, a74
	v_accvgpr_read_b32 v11, a75
	v_accvgpr_read_b32 v12, a76
	v_accvgpr_read_b32 v13, a77
	v_accvgpr_read_b32 v14, a78
	v_accvgpr_read_b32 v15, a79
	v_pk_mul_f32 v[32:33], v[0:1], v[154:155]
	v_pk_mul_f32 v[34:35], v[2:3], v[154:155]
	v_pk_mul_f32 v[36:37], v[4:5], v[154:155]
	v_pk_mul_f32 v[38:39], v[6:7], v[154:155]
	v_pk_mul_f32 v[40:41], v[8:9], v[154:155]
	v_pk_mul_f32 v[42:43], v[10:11], v[154:155]
	v_pk_mul_f32 v[44:45], v[12:13], v[154:155]
	v_pk_mul_f32 v[46:47], v[14:15], v[154:155]
	v_accvgpr_read_b32 v16, a128
	v_accvgpr_read_b32 v17, a129
	v_accvgpr_read_b32 v18, a130
	v_accvgpr_read_b32 v19, a131
	v_accvgpr_read_b32 v20, a132
	v_accvgpr_read_b32 v21, a133
	v_accvgpr_read_b32 v22, a134
	v_accvgpr_read_b32 v23, a135
	v_accvgpr_read_b32 v24, a136
	v_accvgpr_read_b32 v25, a137
	v_accvgpr_read_b32 v26, a138
	v_accvgpr_read_b32 v27, a139
	v_accvgpr_read_b32 v28, a140
	v_accvgpr_read_b32 v29, a141
	v_accvgpr_read_b32 v30, a142
	v_accvgpr_read_b32 v31, a143
	v_exp_f32_e32 v32, v32
	v_exp_f32_e32 v33, v33
	v_exp_f32_e32 v34, v34
	v_exp_f32_e32 v35, v35
	v_exp_f32_e32 v36, v36
	v_exp_f32_e32 v37, v37
	v_exp_f32_e32 v38, v38
	v_exp_f32_e32 v39, v39
	v_exp_f32_e32 v40, v40
	v_exp_f32_e32 v41, v41
	v_exp_f32_e32 v42, v42
	v_exp_f32_e32 v43, v43
	v_exp_f32_e32 v44, v44
	v_exp_f32_e32 v45, v45
	v_exp_f32_e32 v46, v46
	v_exp_f32_e32 v47, v47
	s_nop 0
	v_pk_add_f32 v[32:33], v[32:33], 1.0 op_sel_hi:[1,0]
	v_pk_add_f32 v[34:35], v[34:35], 1.0 op_sel_hi:[1,0]
	v_pk_add_f32 v[36:37], v[36:37], 1.0 op_sel_hi:[1,0]
	v_pk_add_f32 v[38:39], v[38:39], 1.0 op_sel_hi:[1,0]
	v_pk_add_f32 v[40:41], v[40:41], 1.0 op_sel_hi:[1,0]
	v_pk_add_f32 v[42:43], v[42:43], 1.0 op_sel_hi:[1,0]
	v_pk_add_f32 v[44:45], v[44:45], 1.0 op_sel_hi:[1,0]
	v_pk_add_f32 v[46:47], v[46:47], 1.0 op_sel_hi:[1,0]
	v_rcp_f32_e32 v32, v32
	v_rcp_f32_e32 v33, v33
	v_rcp_f32_e32 v34, v34
	v_rcp_f32_e32 v35, v35
	v_rcp_f32_e32 v36, v36
	v_rcp_f32_e32 v37, v37
	v_rcp_f32_e32 v38, v38
	v_rcp_f32_e32 v39, v39
	v_rcp_f32_e32 v40, v40
	v_rcp_f32_e32 v41, v41
	v_rcp_f32_e32 v42, v42
	v_rcp_f32_e32 v43, v43
	v_rcp_f32_e32 v44, v44
	v_rcp_f32_e32 v45, v45
	v_rcp_f32_e32 v46, v46
	v_rcp_f32_e32 v47, v47
	s_nop 0
	v_pk_mul_f32 v[32:33], v[0:1], v[32:33]
	v_pk_mul_f32 v[34:35], v[2:3], v[34:35]
	v_pk_mul_f32 v[36:37], v[4:5], v[36:37]
	v_pk_mul_f32 v[38:39], v[6:7], v[38:39]
	v_pk_mul_f32 v[40:41], v[8:9], v[40:41]
	v_pk_mul_f32 v[42:43], v[10:11], v[42:43]
	v_pk_mul_f32 v[44:45], v[12:13], v[44:45]
	v_pk_mul_f32 v[46:47], v[14:15], v[46:47]
	v_pk_mul_f32 v[32:33], v[32:33], v[16:17]
	v_pk_mul_f32 v[34:35], v[34:35], v[18:19]
	v_pk_mul_f32 v[36:37], v[36:37], v[20:21]
	v_pk_mul_f32 v[38:39], v[38:39], v[22:23]
	v_pk_mul_f32 v[40:41], v[40:41], v[24:25]
	v_pk_mul_f32 v[42:43], v[42:43], v[26:27]
	v_pk_mul_f32 v[44:45], v[44:45], v[28:29]
	v_pk_mul_f32 v[46:47], v[46:47], v[30:31]
	v_cvt_pk_bf16_f32 v48, v32, v33
	v_cvt_pk_bf16_f32 v49, v34, v35
	v_cvt_pk_bf16_f32 v52, v36, v37
	v_cvt_pk_bf16_f32 v53, v38, v39
	v_cvt_pk_bf16_f32 v50, v40, v41
	v_cvt_pk_bf16_f32 v51, v42, v43
	v_cvt_pk_bf16_f32 v54, v44, v45
	v_cvt_pk_bf16_f32 v55, v46, v47
	s_nop 1
	v_permlane32_swap_b32_e32 v48, v50
	v_permlane32_swap_b32_e32 v49, v51
	v_permlane32_swap_b32_e32 v52, v54
	v_permlane32_swap_b32_e32 v53, v55
	s_nop 1
	global_store_dwordx4 v[64:65], v[48:51], off
	global_store_dwordx4 v[64:65], v[52:55], off offset:16
	v_accvgpr_read_b32 v68, a144
	v_accvgpr_read_b32 v69, a145
	v_accvgpr_read_b32 v70, a146
	v_accvgpr_read_b32 v71, a147
	v_accvgpr_read_b32 v72, a148
	v_accvgpr_read_b32 v73, a149
	v_accvgpr_read_b32 v74, a150
	v_accvgpr_read_b32 v75, a151
	v_accvgpr_read_b32 v76, a152
	v_accvgpr_read_b32 v77, a153
	v_accvgpr_read_b32 v78, a154
	v_accvgpr_read_b32 v79, a155
	v_accvgpr_read_b32 v80, a156
	v_accvgpr_read_b32 v81, a157
	v_accvgpr_read_b32 v82, a158
	v_accvgpr_read_b32 v83, a159
	v_pk_mul_f32 v[138:139], v[68:69], v[154:155]
	v_pk_mul_f32 v[140:141], v[70:71], v[154:155]
	v_pk_mul_f32 v[142:143], v[72:73], v[154:155]
	v_pk_mul_f32 v[144:145], v[74:75], v[154:155]
	v_pk_mul_f32 v[146:147], v[76:77], v[154:155]
	v_pk_mul_f32 v[148:149], v[78:79], v[154:155]
	v_pk_mul_f32 v[150:151], v[80:81], v[154:155]
	v_pk_mul_f32 v[152:153], v[82:83], v[154:155]
	v_accvgpr_read_b32 v104, a32
	v_accvgpr_read_b32 v105, a33
	v_accvgpr_read_b32 v106, a34
	v_accvgpr_read_b32 v107, a35
	v_accvgpr_read_b32 v108, a36
	v_accvgpr_read_b32 v109, a37
	v_accvgpr_read_b32 v110, a38
	v_accvgpr_read_b32 v111, a39
	v_accvgpr_read_b32 v112, a40
	v_accvgpr_read_b32 v113, a41
	v_accvgpr_read_b32 v114, a42
	v_accvgpr_read_b32 v115, a43
	v_accvgpr_read_b32 v116, a44
	v_accvgpr_read_b32 v117, a45
	v_accvgpr_read_b32 v118, a46
	v_accvgpr_read_b32 v119, a47
	v_exp_f32_e32 v138, v138
	v_exp_f32_e32 v139, v139
	v_exp_f32_e32 v140, v140
	v_exp_f32_e32 v141, v141
	v_exp_f32_e32 v142, v142
	v_exp_f32_e32 v143, v143
	v_exp_f32_e32 v144, v144
	v_exp_f32_e32 v145, v145
	v_exp_f32_e32 v146, v146
	v_exp_f32_e32 v147, v147
	v_exp_f32_e32 v148, v148
	v_exp_f32_e32 v149, v149
	v_exp_f32_e32 v150, v150
	v_exp_f32_e32 v151, v151
	v_exp_f32_e32 v152, v152
	v_exp_f32_e32 v153, v153
	s_nop 0
	v_pk_add_f32 v[138:139], v[138:139], 1.0 op_sel_hi:[1,0]
	v_pk_add_f32 v[140:141], v[140:141], 1.0 op_sel_hi:[1,0]
	v_pk_add_f32 v[142:143], v[142:143], 1.0 op_sel_hi:[1,0]
	v_pk_add_f32 v[144:145], v[144:145], 1.0 op_sel_hi:[1,0]
	v_pk_add_f32 v[146:147], v[146:147], 1.0 op_sel_hi:[1,0]
	v_pk_add_f32 v[148:149], v[148:149], 1.0 op_sel_hi:[1,0]
	v_pk_add_f32 v[150:151], v[150:151], 1.0 op_sel_hi:[1,0]
	v_pk_add_f32 v[152:153], v[152:153], 1.0 op_sel_hi:[1,0]
	v_rcp_f32_e32 v138, v138
	v_rcp_f32_e32 v139, v139
	v_rcp_f32_e32 v140, v140
	v_rcp_f32_e32 v141, v141
	v_rcp_f32_e32 v142, v142
	v_rcp_f32_e32 v143, v143
	v_rcp_f32_e32 v144, v144
	v_rcp_f32_e32 v145, v145
	v_rcp_f32_e32 v146, v146
	v_rcp_f32_e32 v147, v147
	v_rcp_f32_e32 v148, v148
	v_rcp_f32_e32 v149, v149
	v_rcp_f32_e32 v150, v150
	v_rcp_f32_e32 v151, v151
	v_rcp_f32_e32 v152, v152
	v_rcp_f32_e32 v153, v153
	s_nop 0
	v_pk_mul_f32 v[138:139], v[68:69], v[138:139]
	v_pk_mul_f32 v[140:141], v[70:71], v[140:141]
	v_pk_mul_f32 v[142:143], v[72:73], v[142:143]
	v_pk_mul_f32 v[144:145], v[74:75], v[144:145]
	v_pk_mul_f32 v[146:147], v[76:77], v[146:147]
	v_pk_mul_f32 v[148:149], v[78:79], v[148:149]
	v_pk_mul_f32 v[150:151], v[80:81], v[150:151]
	v_pk_mul_f32 v[152:153], v[82:83], v[152:153]
	v_pk_mul_f32 v[138:139], v[138:139], v[104:105]
	v_pk_mul_f32 v[140:141], v[140:141], v[106:107]
	v_pk_mul_f32 v[142:143], v[142:143], v[108:109]
	v_pk_mul_f32 v[144:145], v[144:145], v[110:111]
	v_pk_mul_f32 v[146:147], v[146:147], v[112:113]
	v_pk_mul_f32 v[148:149], v[148:149], v[114:115]
	v_pk_mul_f32 v[150:151], v[150:151], v[116:117]
	v_pk_mul_f32 v[152:153], v[152:153], v[118:119]
	v_cvt_pk_bf16_f32 v56, v138, v139
	v_cvt_pk_bf16_f32 v57, v140, v141
	v_cvt_pk_bf16_f32 v60, v142, v143
	v_cvt_pk_bf16_f32 v61, v144, v145
	v_cvt_pk_bf16_f32 v58, v146, v147
	v_cvt_pk_bf16_f32 v59, v148, v149
	v_cvt_pk_bf16_f32 v62, v150, v151
	v_cvt_pk_bf16_f32 v63, v152, v153
	s_nop 1
	v_permlane32_swap_b32_e32 v56, v58
	v_permlane32_swap_b32_e32 v57, v59
	v_permlane32_swap_b32_e32 v60, v62
	v_permlane32_swap_b32_e32 v61, v63
	s_nop 1
	global_store_dwordx4 v[96:97], v[56:59], off offset:64
	global_store_dwordx4 v[96:97], v[60:63], off offset:80
	v_accvgpr_read_b32 v0, a160
	v_accvgpr_read_b32 v1, a161
	v_accvgpr_read_b32 v2, a162
	v_accvgpr_read_b32 v3, a163
	v_accvgpr_read_b32 v4, a164
	v_accvgpr_read_b32 v5, a165
	v_accvgpr_read_b32 v6, a166
	v_accvgpr_read_b32 v7, a167
	v_accvgpr_read_b32 v8, a168
	v_accvgpr_read_b32 v9, a169
	v_accvgpr_read_b32 v10, a170
	v_accvgpr_read_b32 v11, a171
	v_accvgpr_read_b32 v12, a172
	v_accvgpr_read_b32 v13, a173
	v_accvgpr_read_b32 v14, a174
	v_accvgpr_read_b32 v15, a175
	v_pk_mul_f32 v[32:33], v[0:1], v[154:155]
	v_pk_mul_f32 v[34:35], v[2:3], v[154:155]
	v_pk_mul_f32 v[36:37], v[4:5], v[154:155]
	v_pk_mul_f32 v[38:39], v[6:7], v[154:155]
	v_pk_mul_f32 v[40:41], v[8:9], v[154:155]
	v_pk_mul_f32 v[42:43], v[10:11], v[154:155]
	v_pk_mul_f32 v[44:45], v[12:13], v[154:155]
	v_pk_mul_f32 v[46:47], v[14:15], v[154:155]
	v_accvgpr_read_b32 v16, a16
	v_accvgpr_read_b32 v17, a17
	v_accvgpr_read_b32 v18, a18
	v_accvgpr_read_b32 v19, a19
	v_accvgpr_read_b32 v20, a20
	v_accvgpr_read_b32 v21, a21
	v_accvgpr_read_b32 v22, a22
	v_accvgpr_read_b32 v23, a23
	v_accvgpr_read_b32 v24, a24
	v_accvgpr_read_b32 v25, a25
	v_accvgpr_read_b32 v26, a26
	v_accvgpr_read_b32 v27, a27
	v_accvgpr_read_b32 v28, a28
	v_accvgpr_read_b32 v29, a29
	v_accvgpr_read_b32 v30, a30
	v_accvgpr_read_b32 v31, a31
	v_exp_f32_e32 v32, v32
	v_exp_f32_e32 v33, v33
	v_exp_f32_e32 v34, v34
	v_exp_f32_e32 v35, v35
	v_exp_f32_e32 v36, v36
	v_exp_f32_e32 v37, v37
	v_exp_f32_e32 v38, v38
	v_exp_f32_e32 v39, v39
	v_exp_f32_e32 v40, v40
	v_exp_f32_e32 v41, v41
	v_exp_f32_e32 v42, v42
	v_exp_f32_e32 v43, v43
	v_exp_f32_e32 v44, v44
	v_exp_f32_e32 v45, v45
	v_exp_f32_e32 v46, v46
	v_exp_f32_e32 v47, v47
	s_nop 0
	v_pk_add_f32 v[32:33], v[32:33], 1.0 op_sel_hi:[1,0]
	v_pk_add_f32 v[34:35], v[34:35], 1.0 op_sel_hi:[1,0]
	v_pk_add_f32 v[36:37], v[36:37], 1.0 op_sel_hi:[1,0]
	v_pk_add_f32 v[38:39], v[38:39], 1.0 op_sel_hi:[1,0]
	v_pk_add_f32 v[40:41], v[40:41], 1.0 op_sel_hi:[1,0]
	v_pk_add_f32 v[42:43], v[42:43], 1.0 op_sel_hi:[1,0]
	v_pk_add_f32 v[44:45], v[44:45], 1.0 op_sel_hi:[1,0]
	v_pk_add_f32 v[46:47], v[46:47], 1.0 op_sel_hi:[1,0]
	v_rcp_f32_e32 v32, v32
	v_rcp_f32_e32 v33, v33
	v_rcp_f32_e32 v34, v34
	v_rcp_f32_e32 v35, v35
	v_rcp_f32_e32 v36, v36
	v_rcp_f32_e32 v37, v37
	v_rcp_f32_e32 v38, v38
	v_rcp_f32_e32 v39, v39
	v_rcp_f32_e32 v40, v40
	v_rcp_f32_e32 v41, v41
	v_rcp_f32_e32 v42, v42
	v_rcp_f32_e32 v43, v43
	v_rcp_f32_e32 v44, v44
	v_rcp_f32_e32 v45, v45
	v_rcp_f32_e32 v46, v46
	v_rcp_f32_e32 v47, v47
	s_nop 0
	v_pk_mul_f32 v[32:33], v[0:1], v[32:33]
	v_pk_mul_f32 v[34:35], v[2:3], v[34:35]
	v_pk_mul_f32 v[36:37], v[4:5], v[36:37]
	v_pk_mul_f32 v[38:39], v[6:7], v[38:39]
	v_pk_mul_f32 v[40:41], v[8:9], v[40:41]
	v_pk_mul_f32 v[42:43], v[10:11], v[42:43]
	v_pk_mul_f32 v[44:45], v[12:13], v[44:45]
	v_pk_mul_f32 v[46:47], v[14:15], v[46:47]
	v_pk_mul_f32 v[32:33], v[32:33], v[16:17]
	v_pk_mul_f32 v[34:35], v[34:35], v[18:19]
	v_pk_mul_f32 v[36:37], v[36:37], v[20:21]
	v_pk_mul_f32 v[38:39], v[38:39], v[22:23]
	v_pk_mul_f32 v[40:41], v[40:41], v[24:25]
	v_pk_mul_f32 v[42:43], v[42:43], v[26:27]
	v_pk_mul_f32 v[44:45], v[44:45], v[28:29]
	v_pk_mul_f32 v[46:47], v[46:47], v[30:31]
	v_cvt_pk_bf16_f32 v48, v32, v33
	v_cvt_pk_bf16_f32 v49, v34, v35
	v_cvt_pk_bf16_f32 v52, v36, v37
	v_cvt_pk_bf16_f32 v53, v38, v39
	v_cvt_pk_bf16_f32 v50, v40, v41
	v_cvt_pk_bf16_f32 v51, v42, v43
	v_cvt_pk_bf16_f32 v54, v44, v45
	v_cvt_pk_bf16_f32 v55, v46, v47
	s_nop 1
	v_permlane32_swap_b32_e32 v48, v50
	v_permlane32_swap_b32_e32 v49, v51
	v_permlane32_swap_b32_e32 v52, v54
	v_permlane32_swap_b32_e32 v53, v55
	s_nop 1
	global_store_dwordx4 v[66:67], v[48:51], off offset:64
	global_store_dwordx4 v[66:67], v[52:55], off offset:80
	v_accvgpr_read_b32 v68, a176
	v_accvgpr_read_b32 v69, a177
	v_accvgpr_read_b32 v70, a178
	v_accvgpr_read_b32 v71, a179
	v_accvgpr_read_b32 v72, a180
	v_accvgpr_read_b32 v73, a181
	v_accvgpr_read_b32 v74, a182
	v_accvgpr_read_b32 v75, a183
	v_accvgpr_read_b32 v76, a184
	v_accvgpr_read_b32 v77, a185
	v_accvgpr_read_b32 v78, a186
	v_accvgpr_read_b32 v79, a187
	v_accvgpr_read_b32 v80, a188
	v_accvgpr_read_b32 v81, a189
	v_accvgpr_read_b32 v82, a190
	v_accvgpr_read_b32 v83, a191
	v_pk_mul_f32 v[138:139], v[68:69], v[154:155]
	v_pk_mul_f32 v[140:141], v[70:71], v[154:155]
	v_pk_mul_f32 v[142:143], v[72:73], v[154:155]
	v_pk_mul_f32 v[144:145], v[74:75], v[154:155]
	v_pk_mul_f32 v[146:147], v[76:77], v[154:155]
	v_pk_mul_f32 v[148:149], v[78:79], v[154:155]
	v_pk_mul_f32 v[150:151], v[80:81], v[154:155]
	v_pk_mul_f32 v[152:153], v[82:83], v[154:155]
	v_accvgpr_read_b32 v104, a0
	v_accvgpr_read_b32 v105, a1
	v_accvgpr_read_b32 v106, a2
	v_accvgpr_read_b32 v107, a3
	v_accvgpr_read_b32 v108, a4
	v_accvgpr_read_b32 v109, a5
	v_accvgpr_read_b32 v110, a6
	v_accvgpr_read_b32 v111, a7
	v_accvgpr_read_b32 v112, a8
	v_accvgpr_read_b32 v113, a9
	v_accvgpr_read_b32 v114, a10
	v_accvgpr_read_b32 v115, a11
	v_accvgpr_read_b32 v116, a12
	v_accvgpr_read_b32 v117, a13
	v_accvgpr_read_b32 v118, a14
	v_accvgpr_read_b32 v119, a15
	v_exp_f32_e32 v138, v138
	v_exp_f32_e32 v139, v139
	v_exp_f32_e32 v140, v140
	v_exp_f32_e32 v141, v141
	v_exp_f32_e32 v142, v142
	v_exp_f32_e32 v143, v143
	v_exp_f32_e32 v144, v144
	v_exp_f32_e32 v145, v145
	v_exp_f32_e32 v146, v146
	v_exp_f32_e32 v147, v147
	v_exp_f32_e32 v148, v148
	v_exp_f32_e32 v149, v149
	v_exp_f32_e32 v150, v150
	v_exp_f32_e32 v151, v151
	v_exp_f32_e32 v152, v152
	v_exp_f32_e32 v153, v153
	s_nop 0
	v_pk_add_f32 v[138:139], v[138:139], 1.0 op_sel_hi:[1,0]
	v_pk_add_f32 v[140:141], v[140:141], 1.0 op_sel_hi:[1,0]
	v_pk_add_f32 v[142:143], v[142:143], 1.0 op_sel_hi:[1,0]
	v_pk_add_f32 v[144:145], v[144:145], 1.0 op_sel_hi:[1,0]
	v_pk_add_f32 v[146:147], v[146:147], 1.0 op_sel_hi:[1,0]
	v_pk_add_f32 v[148:149], v[148:149], 1.0 op_sel_hi:[1,0]
	v_pk_add_f32 v[150:151], v[150:151], 1.0 op_sel_hi:[1,0]
	v_pk_add_f32 v[152:153], v[152:153], 1.0 op_sel_hi:[1,0]
	v_rcp_f32_e32 v138, v138
	v_rcp_f32_e32 v139, v139
	v_rcp_f32_e32 v140, v140
	v_rcp_f32_e32 v141, v141
	v_rcp_f32_e32 v142, v142
	v_rcp_f32_e32 v143, v143
	v_rcp_f32_e32 v144, v144
	v_rcp_f32_e32 v145, v145
	v_rcp_f32_e32 v146, v146
	v_rcp_f32_e32 v147, v147
	v_rcp_f32_e32 v148, v148
	v_rcp_f32_e32 v149, v149
	v_rcp_f32_e32 v150, v150
	v_rcp_f32_e32 v151, v151
	v_rcp_f32_e32 v152, v152
	v_rcp_f32_e32 v153, v153
	s_nop 0
	v_pk_mul_f32 v[138:139], v[68:69], v[138:139]
	v_pk_mul_f32 v[140:141], v[70:71], v[140:141]
	v_pk_mul_f32 v[142:143], v[72:73], v[142:143]
	v_pk_mul_f32 v[144:145], v[74:75], v[144:145]
	v_pk_mul_f32 v[146:147], v[76:77], v[146:147]
	v_pk_mul_f32 v[148:149], v[78:79], v[148:149]
	v_pk_mul_f32 v[150:151], v[80:81], v[150:151]
	v_pk_mul_f32 v[152:153], v[82:83], v[152:153]
	v_pk_mul_f32 v[138:139], v[138:139], v[104:105]
	v_pk_mul_f32 v[140:141], v[140:141], v[106:107]
	v_pk_mul_f32 v[142:143], v[142:143], v[108:109]
	v_pk_mul_f32 v[144:145], v[144:145], v[110:111]
	v_pk_mul_f32 v[146:147], v[146:147], v[112:113]
	v_pk_mul_f32 v[148:149], v[148:149], v[114:115]
	v_pk_mul_f32 v[150:151], v[150:151], v[116:117]
	v_pk_mul_f32 v[152:153], v[152:153], v[118:119]
	v_cvt_pk_bf16_f32 v56, v138, v139
	v_cvt_pk_bf16_f32 v57, v140, v141
	v_cvt_pk_bf16_f32 v60, v142, v143
	v_cvt_pk_bf16_f32 v61, v144, v145
	v_cvt_pk_bf16_f32 v58, v146, v147
	v_cvt_pk_bf16_f32 v59, v148, v149
	v_cvt_pk_bf16_f32 v62, v150, v151
	v_cvt_pk_bf16_f32 v63, v152, v153
	s_nop 1
	v_permlane32_swap_b32_e32 v56, v58
	v_permlane32_swap_b32_e32 v57, v59
	v_permlane32_swap_b32_e32 v60, v62
	v_permlane32_swap_b32_e32 v61, v63
	s_nop 1
	global_store_dwordx4 v[64:65], v[56:59], off offset:64
	global_store_dwordx4 v[64:65], v[60:63], off offset:80
	s_mov_b32 s0, s98
	v_mov_b32_e32 v229, 0x4000
	v_mov_b32_e32 v214, 0x4000
	s_branch .LBB0_161
